# branch-merge GEMM epilogue loads gate/partial rows for two row groups per wait (on top of LN / r2 / attention changes)
# speedup vs baseline: 1.0069x; 1.0040x over previous
.LBB0_588:
	s_add_i32 s10, 0, 0x10000
	v_add_u32_e32 v148, s10, v184
	s_waitcnt lgkmcnt(0)
	ds_read_b128 v[136:139], v148
	ds_read_b128 v[140:143], v148 offset:1024
	ds_read_b128 v[144:147], v148 offset:2048
	ds_read_b128 v[148:151], v148 offset:3072
	s_add_i32 s9, s8, 2
	s_cmp_eq_u32 s2, s8
	v_lshl_add_u64 v[154:155], v[130:131], 0, s[54:55]
	s_cselect_b64 vcc, -1, 0
	v_cndmask_b32_e32 v155, v155, v132, vcc
	v_cndmask_b32_e32 v154, v154, v133, vcc
	v_cndmask_b32_e32 v211, v129, v134, vcc
	v_cndmask_b32_e32 v210, v128, v135, vcc
	v_lshl_add_u64 v[214:215], v[130:131], 0, v[162:163]
	s_add_i32 m0, s28, 0xc000
	ds_read_b128 v[172:175], v185
	ds_read_b128 v[176:179], v185 offset:1024
	ds_read_b128 v[180:183], v185 offset:2048
	ds_read_b128 v[186:189], v185 offset:3072
	ds_read_b128 v[190:193], v185 offset:4096
	ds_read_b128 v[194:197], v185 offset:5120
	ds_read_b128 v[198:201], v185 offset:6144
	ds_read_b128 v[202:205], v185 offset:7168
	global_load_lds_dwordx4 v[214:215], off
	v_lshl_add_u64 v[214:215], v[130:131], 0, v[160:161]
	s_add_i32 m0, s28, 0xe000
	s_nop 0
	global_load_lds_dwordx4 v[214:215], off
	s_waitcnt lgkmcnt(8)
	s_barrier
	s_waitcnt lgkmcnt(0)
	s_setprio 1
	s_waitcnt lgkmcnt(0)
	v_mfma_f32_16x16x32_bf16 v[124:127], v[136:139], v[172:175], v[124:127]
	v_mfma_f32_16x16x32_bf16 v[120:123], v[144:147], v[172:175], v[120:123]
	v_mfma_f32_16x16x32_bf16 v[108:111], v[136:139], v[180:183], v[108:111]
	v_mfma_f32_16x16x32_bf16 v[104:107], v[144:147], v[180:183], v[104:107]
	v_mfma_f32_16x16x32_bf16 v[92:95], v[136:139], v[190:193], v[92:95]
	v_mfma_f32_16x16x32_bf16 v[88:91], v[144:147], v[190:193], v[88:91]
	v_mfma_f32_16x16x32_bf16 v[76:79], v[136:139], v[198:201], v[76:79]
	v_mfma_f32_16x16x32_bf16 v[72:75], v[144:147], v[198:201], v[72:75]
	v_mfma_f32_16x16x32_bf16 v[124:127], v[140:143], v[176:179], v[124:127]
	v_mfma_f32_16x16x32_bf16 v[120:123], v[148:151], v[176:179], v[120:123]
	v_mfma_f32_16x16x32_bf16 v[108:111], v[140:143], v[186:189], v[108:111]
	v_mfma_f32_16x16x32_bf16 v[104:107], v[148:151], v[186:189], v[104:107]
	v_mfma_f32_16x16x32_bf16 v[92:95], v[140:143], v[194:197], v[92:95]
	v_mfma_f32_16x16x32_bf16 v[88:91], v[148:151], v[194:197], v[88:91]
	v_mfma_f32_16x16x32_bf16 v[76:79], v[140:143], v[202:205], v[76:79]
	v_mfma_f32_16x16x32_bf16 v[72:75], v[148:151], v[202:205], v[72:75]
	s_setprio 0
	s_barrier
	s_add_i32 s8, 0, 0x14000
	s_add_i32 s10, s10, s71
	v_add_u32_e32 v152, s8, v184
	v_lshl_add_u64 v[214:215], v[210:211], 0, v[156:157]
	s_mov_b32 m0, s10
	ds_read_b128 v[226:229], v152
	ds_read_b128 v[230:233], v152 offset:1024
	ds_read_b128 v[234:237], v152 offset:2048
	ds_read_b128 v[238:241], v152 offset:3072
	global_load_lds_dwordx4 v[214:215], off
	v_lshl_add_u64 v[216:217], v[210:211], 0, v[158:159]
	s_add_i32 m0, s10, 0x2000
	s_nop 0
	global_load_lds_dwordx4 v[216:217], off
	s_barrier
	s_waitcnt lgkmcnt(0)
	s_setprio 1
	s_waitcnt lgkmcnt(0)
	v_mfma_f32_16x16x32_bf16 v[116:119], v[226:229], v[172:175], v[116:119]
	v_mfma_f32_16x16x32_bf16 v[112:115], v[234:237], v[172:175], v[112:115]
	v_mfma_f32_16x16x32_bf16 v[100:103], v[226:229], v[180:183], v[100:103]
	v_mfma_f32_16x16x32_bf16 v[96:99], v[234:237], v[180:183], v[96:99]
	v_mfma_f32_16x16x32_bf16 v[84:87], v[226:229], v[190:193], v[84:87]
	v_mfma_f32_16x16x32_bf16 v[80:83], v[234:237], v[190:193], v[80:83]
	v_mfma_f32_16x16x32_bf16 v[68:71], v[226:229], v[198:201], v[68:71]
	v_mfma_f32_16x16x32_bf16 v[64:67], v[234:237], v[198:201], v[64:67]
	v_mfma_f32_16x16x32_bf16 v[116:119], v[230:233], v[176:179], v[116:119]
	v_mfma_f32_16x16x32_bf16 v[112:115], v[238:241], v[176:179], v[112:115]
	v_mfma_f32_16x16x32_bf16 v[100:103], v[230:233], v[186:189], v[100:103]
	v_mfma_f32_16x16x32_bf16 v[96:99], v[238:241], v[186:189], v[96:99]
	v_mfma_f32_16x16x32_bf16 v[84:87], v[230:233], v[194:197], v[84:87]
	v_mfma_f32_16x16x32_bf16 v[80:83], v[238:241], v[194:197], v[80:83]
	v_mfma_f32_16x16x32_bf16 v[68:71], v[230:233], v[202:205], v[68:71]
	v_mfma_f32_16x16x32_bf16 v[64:67], v[238:241], v[202:205], v[64:67]
	s_setprio 0
	s_mov_b32 m0, s28
	v_lshl_add_u64 v[218:219], v[154:155], 0, v[156:157]
	s_barrier
	ds_read_b128 v[172:175], v185 offset:16384
	ds_read_b128 v[176:179], v185 offset:17408
	ds_read_b128 v[180:183], v185 offset:18432
	ds_read_b128 v[186:189], v185 offset:19456
	ds_read_b128 v[190:193], v185 offset:20480
	ds_read_b128 v[194:197], v185 offset:21504
	ds_read_b128 v[198:201], v185 offset:22528
	ds_read_b128 v[202:205], v185 offset:23552
	global_load_lds_dwordx4 v[218:219], off
	v_lshl_add_u64 v[220:221], v[154:155], 0, v[158:159]
	s_mov_b32 m0, s29
	s_nop 0
	global_load_lds_dwordx4 v[220:221], off
	s_barrier
	s_waitcnt lgkmcnt(0)
	s_setprio 1
	s_waitcnt lgkmcnt(0)
	v_mfma_f32_16x16x32_bf16 v[60:63], v[136:139], v[172:175], v[60:63]
	v_mfma_f32_16x16x32_bf16 v[56:59], v[144:147], v[172:175], v[56:59]
	v_mfma_f32_16x16x32_bf16 v[44:47], v[136:139], v[180:183], v[44:47]
	v_mfma_f32_16x16x32_bf16 v[40:43], v[144:147], v[180:183], v[40:43]
	v_mfma_f32_16x16x32_bf16 v[28:31], v[136:139], v[190:193], v[28:31]
	v_mfma_f32_16x16x32_bf16 v[24:27], v[144:147], v[190:193], v[24:27]
	v_mfma_f32_16x16x32_bf16 v[12:15], v[136:139], v[198:201], v[12:15]
	v_mfma_f32_16x16x32_bf16 v[8:11], v[144:147], v[198:201], v[8:11]
	v_mfma_f32_16x16x32_bf16 v[60:63], v[140:143], v[176:179], v[60:63]
	v_mfma_f32_16x16x32_bf16 v[56:59], v[148:151], v[176:179], v[56:59]
	v_mfma_f32_16x16x32_bf16 v[44:47], v[140:143], v[186:189], v[44:47]
	v_mfma_f32_16x16x32_bf16 v[40:43], v[148:151], v[186:189], v[40:43]
	v_mfma_f32_16x16x32_bf16 v[28:31], v[140:143], v[194:197], v[28:31]
	v_mfma_f32_16x16x32_bf16 v[24:27], v[148:151], v[194:197], v[24:27]
	v_mfma_f32_16x16x32_bf16 v[12:15], v[140:143], v[202:205], v[12:15]
	v_mfma_f32_16x16x32_bf16 v[8:11], v[148:151], v[202:205], v[8:11]
	s_setprio 0
	s_barrier
	v_lshl_add_u64 v[136:137], v[210:211], 0, s[16:17]
	s_add_i32 s8, s8, s71
	v_lshl_add_u64 v[210:211], v[136:137], 0, v[156:157]
	s_mov_b32 m0, s8
	v_lshl_add_u64 v[224:225], v[136:137], 0, v[158:159]
	global_load_lds_dwordx4 v[210:211], off
	s_add_i32 m0, s8, 0x2000
	s_nop 0
	global_load_lds_dwordx4 v[224:225], off
	s_waitcnt vmcnt(6)
	s_barrier
	s_setprio 1
	v_mfma_f32_16x16x32_bf16 v[52:55], v[226:229], v[172:175], v[52:55]
	v_mfma_f32_16x16x32_bf16 v[48:51], v[234:237], v[172:175], v[48:51]
	v_mfma_f32_16x16x32_bf16 v[36:39], v[226:229], v[180:183], v[36:39]
	v_mfma_f32_16x16x32_bf16 v[32:35], v[234:237], v[180:183], v[32:35]
	v_mfma_f32_16x16x32_bf16 v[20:23], v[226:229], v[190:193], v[20:23]
	v_mfma_f32_16x16x32_bf16 v[16:19], v[234:237], v[190:193], v[16:19]
	v_mfma_f32_16x16x32_bf16 v[4:7], v[226:229], v[198:201], v[4:7]
	v_mfma_f32_16x16x32_bf16 v[0:3], v[234:237], v[198:201], v[0:3]
	v_mfma_f32_16x16x32_bf16 v[52:55], v[230:233], v[176:179], v[52:55]
	v_mfma_f32_16x16x32_bf16 v[48:51], v[238:241], v[176:179], v[48:51]
	v_mfma_f32_16x16x32_bf16 v[36:39], v[230:233], v[186:189], v[36:39]
	v_mfma_f32_16x16x32_bf16 v[32:35], v[238:241], v[186:189], v[32:35]
	v_mfma_f32_16x16x32_bf16 v[20:23], v[230:233], v[194:197], v[20:23]
	v_mfma_f32_16x16x32_bf16 v[16:19], v[238:241], v[194:197], v[16:19]
	v_mfma_f32_16x16x32_bf16 v[4:7], v[230:233], v[202:205], v[4:7]
	v_mfma_f32_16x16x32_bf16 v[0:3], v[238:241], v[202:205], v[0:3]
	s_setprio 0
	s_add_i32 s8, 0, 0x18000
	v_add_u32_e32 v148, s8, v184
	s_barrier
	ds_read_b128 v[136:139], v148
	ds_read_b128 v[140:143], v148 offset:1024
	ds_read_b128 v[144:147], v148 offset:2048
	ds_read_b128 v[148:151], v148 offset:3072
	v_lshl_add_u64 v[154:155], v[154:155], 0, s[16:17]
	s_mov_b32 m0, s35
	v_lshl_add_u64 v[226:227], v[154:155], 0, v[156:157]
	ds_read_b128 v[172:175], v185 offset:32768
	ds_read_b128 v[176:179], v185 offset:33792
	ds_read_b128 v[180:183], v185 offset:34816
	ds_read_b128 v[186:189], v185 offset:35840
	ds_read_b128 v[190:193], v185 offset:36864
	ds_read_b128 v[194:197], v185 offset:37888
	ds_read_b128 v[198:201], v185 offset:38912
	ds_read_b128 v[202:205], v185 offset:39936
	global_load_lds_dwordx4 v[226:227], off
	v_lshl_add_u64 v[154:155], v[154:155], 0, v[158:159]
	s_mov_b32 m0, s74
	s_nop 0
	global_load_lds_dwordx4 v[154:155], off
	s_waitcnt lgkmcnt(8)
	s_barrier
	s_waitcnt lgkmcnt(0)
	s_setprio 1
	s_waitcnt lgkmcnt(0)
	v_mfma_f32_16x16x32_bf16 v[124:127], v[136:139], v[172:175], v[124:127]
	v_mfma_f32_16x16x32_bf16 v[120:123], v[144:147], v[172:175], v[120:123]
	v_mfma_f32_16x16x32_bf16 v[108:111], v[136:139], v[180:183], v[108:111]
	v_mfma_f32_16x16x32_bf16 v[104:107], v[144:147], v[180:183], v[104:107]
	v_mfma_f32_16x16x32_bf16 v[92:95], v[136:139], v[190:193], v[92:95]
	v_mfma_f32_16x16x32_bf16 v[88:91], v[144:147], v[190:193], v[88:91]
	v_mfma_f32_16x16x32_bf16 v[76:79], v[136:139], v[198:201], v[76:79]
	v_mfma_f32_16x16x32_bf16 v[72:75], v[144:147], v[198:201], v[72:75]
	v_mfma_f32_16x16x32_bf16 v[124:127], v[140:143], v[176:179], v[124:127]
	v_mfma_f32_16x16x32_bf16 v[120:123], v[148:151], v[176:179], v[120:123]
	v_mfma_f32_16x16x32_bf16 v[108:111], v[140:143], v[186:189], v[108:111]
	v_mfma_f32_16x16x32_bf16 v[104:107], v[148:151], v[186:189], v[104:107]
	v_mfma_f32_16x16x32_bf16 v[92:95], v[140:143], v[194:197], v[92:95]
	v_mfma_f32_16x16x32_bf16 v[88:91], v[148:151], v[194:197], v[88:91]
	v_mfma_f32_16x16x32_bf16 v[76:79], v[140:143], v[202:205], v[76:79]
	v_mfma_f32_16x16x32_bf16 v[72:75], v[148:151], v[202:205], v[72:75]
	s_setprio 0
	s_barrier
	s_add_i32 s10, 0, 0x1c000
	s_add_i32 s8, s8, s71
	v_add_u32_e32 v152, s10, v184
	v_lshl_add_u64 v[154:155], v[214:215], 0, s[54:55]
	s_mov_b32 m0, s8
	ds_read_b128 v[226:229], v152
	ds_read_b128 v[230:233], v152 offset:1024
	ds_read_b128 v[234:237], v152 offset:2048
	ds_read_b128 v[238:241], v152 offset:3072
	global_load_lds_dwordx4 v[154:155], off
	v_lshl_add_u64 v[154:155], v[216:217], 0, s[54:55]
	s_add_i32 m0, s8, 0x2000
	s_nop 0
	global_load_lds_dwordx4 v[154:155], off
	s_barrier
	s_waitcnt lgkmcnt(0)
	s_setprio 1
	s_waitcnt lgkmcnt(0)
	v_mfma_f32_16x16x32_bf16 v[116:119], v[226:229], v[172:175], v[116:119]
	v_mfma_f32_16x16x32_bf16 v[112:115], v[234:237], v[172:175], v[112:115]
	v_mfma_f32_16x16x32_bf16 v[100:103], v[226:229], v[180:183], v[100:103]
	v_mfma_f32_16x16x32_bf16 v[96:99], v[234:237], v[180:183], v[96:99]
	v_mfma_f32_16x16x32_bf16 v[84:87], v[226:229], v[190:193], v[84:87]
	v_mfma_f32_16x16x32_bf16 v[80:83], v[234:237], v[190:193], v[80:83]
	v_mfma_f32_16x16x32_bf16 v[68:71], v[226:229], v[198:201], v[68:71]
	v_mfma_f32_16x16x32_bf16 v[64:67], v[234:237], v[198:201], v[64:67]
	v_mfma_f32_16x16x32_bf16 v[116:119], v[230:233], v[176:179], v[116:119]
	v_mfma_f32_16x16x32_bf16 v[112:115], v[238:241], v[176:179], v[112:115]
	v_mfma_f32_16x16x32_bf16 v[100:103], v[230:233], v[186:189], v[100:103]
	v_mfma_f32_16x16x32_bf16 v[96:99], v[238:241], v[186:189], v[96:99]
	v_mfma_f32_16x16x32_bf16 v[84:87], v[230:233], v[194:197], v[84:87]
	v_mfma_f32_16x16x32_bf16 v[80:83], v[238:241], v[194:197], v[80:83]
	v_mfma_f32_16x16x32_bf16 v[68:71], v[230:233], v[202:205], v[68:71]
	v_mfma_f32_16x16x32_bf16 v[64:67], v[238:241], v[202:205], v[64:67]
	s_setprio 0
	s_mov_b32 m0, s4
	v_lshl_add_u64 v[154:155], v[218:219], 0, s[54:55]
	s_barrier
	ds_read_b128 v[172:175], v185 offset:49152
	ds_read_b128 v[176:179], v185 offset:50176
	ds_read_b128 v[180:183], v185 offset:51200
	ds_read_b128 v[186:189], v185 offset:52224
	ds_read_b128 v[190:193], v185 offset:53248
	ds_read_b128 v[194:197], v185 offset:54272
	ds_read_b128 v[198:201], v185 offset:55296
	ds_read_b128 v[202:205], v185 offset:56320
	global_load_lds_dwordx4 v[154:155], off
	v_lshl_add_u64 v[154:155], v[220:221], 0, s[54:55]
	s_mov_b32 m0, s5
	s_nop 0
	global_load_lds_dwordx4 v[154:155], off
	s_barrier
	s_waitcnt lgkmcnt(0)
	s_setprio 1
	s_waitcnt lgkmcnt(0)
	v_mfma_f32_16x16x32_bf16 v[60:63], v[136:139], v[172:175], v[60:63]
	v_mfma_f32_16x16x32_bf16 v[56:59], v[144:147], v[172:175], v[56:59]
	v_mfma_f32_16x16x32_bf16 v[44:47], v[136:139], v[180:183], v[44:47]
	v_mfma_f32_16x16x32_bf16 v[40:43], v[144:147], v[180:183], v[40:43]
	v_mfma_f32_16x16x32_bf16 v[28:31], v[136:139], v[190:193], v[28:31]
	v_mfma_f32_16x16x32_bf16 v[24:27], v[144:147], v[190:193], v[24:27]
	v_mfma_f32_16x16x32_bf16 v[12:15], v[136:139], v[198:201], v[12:15]
	v_mfma_f32_16x16x32_bf16 v[8:11], v[144:147], v[198:201], v[8:11]
	v_mfma_f32_16x16x32_bf16 v[60:63], v[140:143], v[176:179], v[60:63]
	v_mfma_f32_16x16x32_bf16 v[56:59], v[148:151], v[176:179], v[56:59]
	v_mfma_f32_16x16x32_bf16 v[44:47], v[140:143], v[186:189], v[44:47]
	v_mfma_f32_16x16x32_bf16 v[40:43], v[148:151], v[186:189], v[40:43]
	v_mfma_f32_16x16x32_bf16 v[28:31], v[140:143], v[194:197], v[28:31]
	v_mfma_f32_16x16x32_bf16 v[24:27], v[148:151], v[194:197], v[24:27]
	v_mfma_f32_16x16x32_bf16 v[12:15], v[140:143], v[202:205], v[12:15]
	v_mfma_f32_16x16x32_bf16 v[8:11], v[148:151], v[202:205], v[8:11]
	s_setprio 0
	s_barrier
	s_add_i32 s8, s10, s71
	v_lshl_add_u64 v[136:137], v[210:211], 0, s[54:55]
	s_mov_b32 m0, s8
	s_nop 0
	global_load_lds_dwordx4 v[136:137], off
	v_lshl_add_u64 v[136:137], v[224:225], 0, s[54:55]
	s_add_i32 m0, s8, 0x2000
	s_nop 0
	global_load_lds_dwordx4 v[136:137], off
	s_waitcnt vmcnt(6)
	s_barrier
	s_setprio 1
	v_mfma_f32_16x16x32_bf16 v[52:55], v[226:229], v[172:175], v[52:55]
	v_mfma_f32_16x16x32_bf16 v[48:51], v[234:237], v[172:175], v[48:51]
	v_mfma_f32_16x16x32_bf16 v[36:39], v[226:229], v[180:183], v[36:39]
	v_mfma_f32_16x16x32_bf16 v[32:35], v[234:237], v[180:183], v[32:35]
	v_mfma_f32_16x16x32_bf16 v[20:23], v[226:229], v[190:193], v[20:23]
	v_mfma_f32_16x16x32_bf16 v[16:19], v[234:237], v[190:193], v[16:19]
	v_mfma_f32_16x16x32_bf16 v[4:7], v[226:229], v[198:201], v[4:7]
	v_mfma_f32_16x16x32_bf16 v[0:3], v[234:237], v[198:201], v[0:3]
	v_mfma_f32_16x16x32_bf16 v[52:55], v[230:233], v[176:179], v[52:55]
	v_mfma_f32_16x16x32_bf16 v[48:51], v[238:241], v[176:179], v[48:51]
	v_mfma_f32_16x16x32_bf16 v[36:39], v[230:233], v[186:189], v[36:39]
	v_mfma_f32_16x16x32_bf16 v[32:35], v[238:241], v[186:189], v[32:35]
	v_mfma_f32_16x16x32_bf16 v[20:23], v[230:233], v[194:197], v[20:23]
	v_mfma_f32_16x16x32_bf16 v[16:19], v[238:241], v[194:197], v[16:19]
	v_mfma_f32_16x16x32_bf16 v[4:7], v[230:233], v[202:205], v[4:7]
	v_mfma_f32_16x16x32_bf16 v[0:3], v[238:241], v[202:205], v[0:3]
	s_setprio 0
	v_lshl_add_u64 v[128:129], v[128:129], 0, s[52:53]
	v_lshl_add_u64 v[130:131], v[130:131], 0, s[52:53]
	s_cmp_ge_i32 s9, s12
	s_mov_b32 s8, s9
	s_barrier
	s_cbranch_scc0 .LBB0_588
	v_mov_b32_e32 v191, v206
	s_lshl_b32 s40, s27, 8
	v_readfirstlane_b32 s2, v191
	s_ashr_i32 s26, s2, 2
	s_bfe_u32 s89, s2, 0x20006
	v_bfe_u32 v188, v191, 4, 2
	s_andn2_b32 s26, s26, 63
	v_and_b32_e32 v189, 15, v191
	s_add_i32 s86, s26, s40
	s_lshl_b32 s41, s89, 5
	v_lshlrev_b32_e32 v190, 2, v188
	v_or_b32_e32 v172, s86, v189
	v_or_b32_e32 v187, s41, v190
	v_lshl_or_b32 v186, v188, 3, s41
	s_cmp_lt_i32 s93, 3
	s_mov_b64 s[8:9], -1
	s_cbranch_scc1 .LBB0_1004
	s_cmp_lt_i32 s93, 4
	s_cbranch_scc1 .LBB0_906
	s_cmp_lt_i32 s93, 6
	s_cbranch_scc1 .LBB0_731
	s_cmp_lt_i32 s93, 9
	s_cbranch_scc0 .LBB0_730
	s_cmp_eq_u32 s93, 7
	s_movk_i32 s2, 0x800
	s_cselect_b32 s2, 0x400, s2
	s_cmp_lg_u32 s93, 6
	s_cselect_b32 s2, s2, 0
	v_lshl_or_b32 v174, s14, 8, v186
	v_mov_b64_e32 v[128:129], s[44:45]
	s_movk_i32 s8, 0x1800
	v_mad_i64_i32 v[128:129], s[8:9], v172, s8, v[128:129]
	s_lshl_b32 s2, s2, 1
	v_ashrrev_i32_e32 v175, 31, v174
	v_lshl_add_u64 v[128:129], v[128:129], 0, s[2:3]
	v_lshlrev_b64 v[176:177], 1, v[174:175]
	v_lshl_add_u64 v[128:129], v[128:129], 0, v[176:177]
	v_mov_b64_e32 v[214:215], v[128:129]
	flat_load_dwordx4 v[140:143], v[128:129]
	v_ashrrev_i32_e32 v173, 31, v172
	v_readlane_b32 s8, v254, 43
	v_lshlrev_b64 v[178:179], 11, v[172:173]
	v_readlane_b32 s9, v254, 44
	s_cmp_eq_u32 s93, 8
	s_cselect_b64 s[10:11], -1, 0
	v_lshl_add_u64 v[130:131], s[8:9], 0, v[178:179]
	s_cmp_lg_u32 s93, 8
	v_lshl_add_u64 v[144:145], v[130:131], 0, v[176:177]
	v_mov_b64_e32 v[216:217], v[144:145]
	s_cbranch_scc1 .LBB0_595
	flat_load_dwordx4 v[132:135], v[144:145]

.LBB0_597:
	s_mov_b32 s98, 0x18000
	s_mov_b32 s99, 0
	v_lshl_add_u64 v[218:219], v[214:215], 0, s[98:99]
	global_load_dwordx4 v[226:229], v[218:219], off
	global_load_dwordx4 v[230:233], v[218:219], off offset:256
	s_cmp_lg_u32 s93, 8
	s_cbranch_scc1 .Lbrp_skip_0
	s_mov_b32 s98, 0x8000
	v_lshl_add_u64 v[218:219], v[216:217], 0, s[98:99]
	global_load_dwordx4 v[234:237], v[218:219], off
	global_load_dwordx4 v[238:241], v[218:219], off offset:256

.LBB0_610:
	v_lshl_add_u64 v[140:141], s[18:19], 0, v[180:181]
	v_lshl_add_u64 v[140:141], v[140:141], 0, v[182:183]
	v_cvt_pk_bf16_f32 v136, v144, v145
	v_cvt_pk_bf16_f32 v137, v146, v147
	v_cvt_pk_bf16_f32 v138, v148, v149
	v_cvt_pk_bf16_f32 v139, v150, v151
	v_lshl_add_u64 v[140:141], v[140:141], 0, v[176:177]
	flat_store_dwordx4 v[140:141], v[136:139] offset:256
	v_or_b32_e32 v146, 16, v172
	s_movk_i32 s10, 0x1800
	v_mov_b64_e32 v[136:137], s[44:45]
	v_mad_i64_i32 v[136:137], s[10:11], v146, s10, v[136:137]
	v_lshl_add_u64 v[136:137], v[136:137], 0, s[2:3]
	v_lshl_add_u64 v[136:137], v[136:137], 0, v[176:177]
	v_ashrrev_i32_e32 v147, 31, v146
	v_readlane_b32 s10, v254, 43
	v_lshlrev_b64 v[178:179], 11, v[146:147]
	v_readlane_b32 s11, v254, 44
	s_and_b64 vcc, exec, s[8:9]
	s_nop 0
	v_lshl_add_u64 v[138:139], s[10:11], 0, v[178:179]
	v_lshl_add_u64 v[144:145], v[138:139], 0, v[176:177]
	s_cbranch_vccnz .LBB0_612
.LBB0_612:
	s_nop 0
	s_and_b64 vcc, exec, s[8:9]
	s_cbranch_vccnz .LBB0_614
.LBB0_614:
	v_lshlrev_b64 v[180:181], 12, v[146:147]
	v_mov_b64_e32 v[140:141], v[226:227]
	v_mov_b64_e32 v[142:143], v[228:229]
	v_mov_b64_e32 v[136:137], v[230:231]
	v_mov_b64_e32 v[138:139], v[232:233]
	v_mov_b64_e32 v[132:133], v[234:235]
	v_mov_b64_e32 v[134:135], v[236:237]
	v_mov_b64_e32 v[128:129], v[238:239]
	v_mov_b64_e32 v[130:131], v[240:241]
	v_lshlrev_b32_e32 v146, 16, v140
	v_and_b32_e32 v147, 0xffff0000, v140
	v_lshlrev_b32_e32 v140, 16, v141
	v_and_b32_e32 v141, 0xffff0000, v141
	v_lshlrev_b32_e32 v148, 16, v142
	v_and_b32_e32 v149, 0xffff0000, v142
	v_lshlrev_b32_e32 v150, 16, v143
	v_and_b32_e32 v151, 0xffff0000, v143
	v_pk_mul_f32 v[140:141], v[110:111], v[140:141]
	v_pk_mul_f32 v[142:143], v[108:109], v[146:147]
	v_pk_mul_f32 v[146:147], v[106:107], v[150:151]
	v_pk_mul_f32 v[148:149], v[104:105], v[148:149]
	s_cmp_lt_i32 s93, 7
	s_mov_b64 s[10:11], -1
	s_cbranch_scc1 .LBB0_620
	s_cmp_lg_u32 s93, 7
	s_cbranch_scc0 .LBB0_617
	v_lshlrev_b32_e32 v150, 16, v132
	v_and_b32_e32 v151, 0xffff0000, v132
	v_pk_add_f32 v[150:151], v[142:143], v[150:151]
	v_lshlrev_b32_e32 v192, 16, v135
	v_and_b32_e32 v193, 0xffff0000, v135
	v_pk_add_f32 v[196:197], v[146:147], v[192:193]
	v_cvt_pk_bf16_f32 v192, v150, v151
	v_lshl_add_u64 v[150:151], s[18:19], 0, v[180:181]
	v_lshlrev_b32_e32 v154, 16, v133
	v_and_b32_e32 v155, 0xffff0000, v133
	v_lshlrev_b32_e32 v182, 16, v134
	v_and_b32_e32 v183, 0xffff0000, v134
	v_lshl_add_u64 v[150:151], v[174:175], 1, v[150:151]
	v_pk_add_f32 v[154:155], v[140:141], v[154:155]
	v_pk_add_f32 v[182:183], v[148:149], v[182:183]
	v_add_co_u32_e32 v150, vcc, 0xbf00000, v150
	v_cvt_pk_bf16_f32 v193, v154, v155
	v_cvt_pk_bf16_f32 v194, v182, v183
	v_cvt_pk_bf16_f32 v195, v196, v197
	v_addc_co_u32_e32 v151, vcc, 0, v151, vcc
	flat_store_dwordx4 v[150:151], v[192:195] offset:2048
	s_mov_b64 s[10:11], 0

.LBB0_631:
	v_lshlrev_b64 v[180:181], 12, v[146:147]
	s_mov_b32 s98, 0x48000
	s_mov_b32 s99, 0
	v_lshl_add_u64 v[218:219], v[214:215], 0, s[98:99]
	global_load_dwordx4 v[226:229], v[218:219], off
	global_load_dwordx4 v[230:233], v[218:219], off offset:256
	s_cmp_lg_u32 s93, 8
	s_cbranch_scc1 .Lbrp_skip_2
	s_mov_b32 s98, 0x18000
	v_lshl_add_u64 v[218:219], v[216:217], 0, s[98:99]
	global_load_dwordx4 v[234:237], v[218:219], off
	global_load_dwordx4 v[238:241], v[218:219], off offset:256
.Lbrp_skip_2:
	s_waitcnt vmcnt(0) lgkmcnt(0)
	v_lshlrev_b32_e32 v146, 16, v140
	v_and_b32_e32 v147, 0xffff0000, v140
	v_lshlrev_b32_e32 v140, 16, v141
	v_and_b32_e32 v141, 0xffff0000, v141
	v_lshlrev_b32_e32 v148, 16, v142
	v_and_b32_e32 v149, 0xffff0000, v142
	v_lshlrev_b32_e32 v150, 16, v143
	v_and_b32_e32 v151, 0xffff0000, v143
	v_pk_mul_f32 v[140:141], v[94:95], v[140:141]
	v_pk_mul_f32 v[142:143], v[92:93], v[146:147]
	v_pk_mul_f32 v[146:147], v[90:91], v[150:151]
	v_pk_mul_f32 v[148:149], v[88:89], v[148:149]
	s_cmp_lt_i32 s93, 7
	s_mov_b64 s[10:11], -1
	s_cbranch_scc1 .LBB0_637
	s_cmp_lg_u32 s93, 7
	s_cbranch_scc0 .LBB0_634
	v_lshlrev_b32_e32 v150, 16, v132
	v_and_b32_e32 v151, 0xffff0000, v132
	v_pk_add_f32 v[150:151], v[142:143], v[150:151]
	v_lshlrev_b32_e32 v192, 16, v135
	v_and_b32_e32 v193, 0xffff0000, v135
	v_pk_add_f32 v[196:197], v[146:147], v[192:193]
	v_cvt_pk_bf16_f32 v192, v150, v151
	v_lshl_add_u64 v[150:151], s[18:19], 0, v[180:181]
	v_lshlrev_b32_e32 v154, 16, v133
	v_and_b32_e32 v155, 0xffff0000, v133
	v_lshlrev_b32_e32 v182, 16, v134
	v_and_b32_e32 v183, 0xffff0000, v134
	v_lshl_add_u64 v[150:151], v[174:175], 1, v[150:151]
	v_pk_add_f32 v[154:155], v[140:141], v[154:155]
	v_pk_add_f32 v[182:183], v[148:149], v[182:183]
	v_add_co_u32_e32 v150, vcc, 0xbf00000, v150
	v_cvt_pk_bf16_f32 v193, v154, v155
	v_cvt_pk_bf16_f32 v194, v182, v183
	v_cvt_pk_bf16_f32 v195, v196, v197
	v_addc_co_u32_e32 v151, vcc, 0, v151, vcc
	flat_store_dwordx4 v[150:151], v[192:195] offset:2048
	s_mov_b64 s[10:11], 0

.LBB0_644:
	v_lshl_add_u64 v[140:141], s[18:19], 0, v[180:181]
	v_lshl_add_u64 v[140:141], v[140:141], 0, v[182:183]
	v_cvt_pk_bf16_f32 v136, v144, v145
	v_cvt_pk_bf16_f32 v137, v146, v147
	v_cvt_pk_bf16_f32 v138, v148, v149
	v_cvt_pk_bf16_f32 v139, v150, v151
	v_lshl_add_u64 v[140:141], v[140:141], 0, v[176:177]
	flat_store_dwordx4 v[140:141], v[136:139] offset:256
	v_or_b32_e32 v146, 48, v172
	s_movk_i32 s10, 0x1800
	v_mov_b64_e32 v[136:137], s[44:45]
	v_mad_i64_i32 v[136:137], s[10:11], v146, s10, v[136:137]
	v_lshl_add_u64 v[136:137], v[136:137], 0, s[2:3]
	v_lshl_add_u64 v[136:137], v[136:137], 0, v[176:177]
	v_ashrrev_i32_e32 v147, 31, v146
	v_readlane_b32 s10, v254, 43
	v_lshlrev_b64 v[178:179], 11, v[146:147]
	v_readlane_b32 s11, v254, 44
	s_and_b64 vcc, exec, s[8:9]
	s_nop 0
	v_lshl_add_u64 v[138:139], s[10:11], 0, v[178:179]
	v_lshl_add_u64 v[144:145], v[138:139], 0, v[176:177]
	s_cbranch_vccnz .LBB0_646

.LBB0_648:
	v_lshlrev_b64 v[180:181], 12, v[146:147]
	v_mov_b64_e32 v[140:141], v[226:227]
	v_mov_b64_e32 v[142:143], v[228:229]
	v_mov_b64_e32 v[136:137], v[230:231]
	v_mov_b64_e32 v[138:139], v[232:233]
	v_mov_b64_e32 v[132:133], v[234:235]
	v_mov_b64_e32 v[134:135], v[236:237]
	v_mov_b64_e32 v[128:129], v[238:239]
	v_mov_b64_e32 v[130:131], v[240:241]
	v_lshlrev_b32_e32 v146, 16, v140
	v_and_b32_e32 v147, 0xffff0000, v140
	v_lshlrev_b32_e32 v140, 16, v141
	v_and_b32_e32 v141, 0xffff0000, v141
	v_lshlrev_b32_e32 v148, 16, v142
	v_and_b32_e32 v149, 0xffff0000, v142
	v_lshlrev_b32_e32 v150, 16, v143
	v_and_b32_e32 v151, 0xffff0000, v143
	v_pk_mul_f32 v[140:141], v[78:79], v[140:141]
	v_pk_mul_f32 v[142:143], v[76:77], v[146:147]
	v_pk_mul_f32 v[146:147], v[74:75], v[150:151]
	v_pk_mul_f32 v[148:149], v[72:73], v[148:149]
	s_cmp_lt_i32 s93, 7
	s_mov_b64 s[10:11], -1
	s_cbranch_scc1 .LBB0_654
	s_cmp_lg_u32 s93, 7
	s_cbranch_scc0 .LBB0_651
	v_lshlrev_b32_e32 v150, 16, v132
	v_and_b32_e32 v151, 0xffff0000, v132
	v_pk_add_f32 v[150:151], v[142:143], v[150:151]
	v_lshlrev_b32_e32 v192, 16, v135
	v_and_b32_e32 v193, 0xffff0000, v135
	v_pk_add_f32 v[196:197], v[146:147], v[192:193]
	v_cvt_pk_bf16_f32 v192, v150, v151
	v_lshl_add_u64 v[150:151], s[18:19], 0, v[180:181]
	v_lshlrev_b32_e32 v154, 16, v133
	v_and_b32_e32 v155, 0xffff0000, v133
	v_lshlrev_b32_e32 v182, 16, v134
	v_and_b32_e32 v183, 0xffff0000, v134
	v_lshl_add_u64 v[150:151], v[174:175], 1, v[150:151]
	v_pk_add_f32 v[154:155], v[140:141], v[154:155]
	v_pk_add_f32 v[182:183], v[148:149], v[182:183]
	v_add_co_u32_e32 v150, vcc, 0xbf00000, v150
	v_cvt_pk_bf16_f32 v193, v154, v155
	v_cvt_pk_bf16_f32 v194, v182, v183
	v_cvt_pk_bf16_f32 v195, v196, v197
	v_addc_co_u32_e32 v151, vcc, 0, v151, vcc
	flat_store_dwordx4 v[150:151], v[192:195] offset:2048
	s_mov_b64 s[10:11], 0

.LBB0_665:
	v_lshlrev_b64 v[180:181], 12, v[146:147]
	s_mov_b32 s98, 0xd8000
	s_mov_b32 s99, 0
	v_lshl_add_u64 v[218:219], v[214:215], 0, s[98:99]
	global_load_dwordx4 v[226:229], v[218:219], off
	global_load_dwordx4 v[230:233], v[218:219], off offset:256
	s_cmp_lg_u32 s93, 8
	s_cbranch_scc1 .Lbrp_skip_4
	s_mov_b32 s98, 0x48000
	v_lshl_add_u64 v[218:219], v[216:217], 0, s[98:99]
	global_load_dwordx4 v[234:237], v[218:219], off
	global_load_dwordx4 v[238:241], v[218:219], off offset:256
.Lbrp_skip_4:
	s_waitcnt vmcnt(0) lgkmcnt(0)
	v_lshlrev_b32_e32 v146, 16, v140
	v_and_b32_e32 v147, 0xffff0000, v140
	v_lshlrev_b32_e32 v140, 16, v141
	v_and_b32_e32 v141, 0xffff0000, v141
	v_lshlrev_b32_e32 v148, 16, v142
	v_and_b32_e32 v149, 0xffff0000, v142
	v_lshlrev_b32_e32 v150, 16, v143
	v_and_b32_e32 v151, 0xffff0000, v143
	v_pk_mul_f32 v[140:141], v[62:63], v[140:141]
	v_pk_mul_f32 v[142:143], v[60:61], v[146:147]
	v_pk_mul_f32 v[146:147], v[58:59], v[150:151]
	v_pk_mul_f32 v[148:149], v[56:57], v[148:149]
	s_cmp_lt_i32 s93, 7
	s_mov_b64 s[10:11], -1
	s_cbranch_scc1 .LBB0_671
	s_cmp_lg_u32 s93, 7
	s_cbranch_scc0 .LBB0_668
	v_lshlrev_b32_e32 v150, 16, v132
	v_and_b32_e32 v151, 0xffff0000, v132
	v_pk_add_f32 v[150:151], v[142:143], v[150:151]
	v_lshlrev_b32_e32 v192, 16, v135
	v_and_b32_e32 v193, 0xffff0000, v135
	v_pk_add_f32 v[196:197], v[146:147], v[192:193]
	v_cvt_pk_bf16_f32 v192, v150, v151
	v_lshl_add_u64 v[150:151], s[18:19], 0, v[180:181]
	v_lshlrev_b32_e32 v154, 16, v133
	v_and_b32_e32 v155, 0xffff0000, v133
	v_lshlrev_b32_e32 v182, 16, v134
	v_and_b32_e32 v183, 0xffff0000, v134
	v_lshl_add_u64 v[150:151], v[174:175], 1, v[150:151]
	v_pk_add_f32 v[154:155], v[140:141], v[154:155]
	v_pk_add_f32 v[182:183], v[148:149], v[182:183]
	v_add_co_u32_e32 v150, vcc, 0xbf00000, v150
	v_cvt_pk_bf16_f32 v193, v154, v155
	v_cvt_pk_bf16_f32 v194, v182, v183
	v_cvt_pk_bf16_f32 v195, v196, v197
	v_addc_co_u32_e32 v151, vcc, 0, v151, vcc
	flat_store_dwordx4 v[150:151], v[192:195] offset:2048
	s_mov_b64 s[10:11], 0

.LBB0_678:
	v_lshl_add_u64 v[140:141], s[18:19], 0, v[180:181]
	v_lshl_add_u64 v[140:141], v[140:141], 0, v[182:183]
	v_cvt_pk_bf16_f32 v136, v144, v145
	v_cvt_pk_bf16_f32 v137, v146, v147
	v_cvt_pk_bf16_f32 v138, v148, v149
	v_cvt_pk_bf16_f32 v139, v150, v151
	v_lshl_add_u64 v[140:141], v[140:141], 0, v[176:177]
	flat_store_dwordx4 v[140:141], v[136:139] offset:256
	v_add_u32_e32 v146, 0x90, v172
	s_movk_i32 s10, 0x1800
	v_mov_b64_e32 v[136:137], s[44:45]
	v_mad_i64_i32 v[136:137], s[10:11], v146, s10, v[136:137]
	v_lshl_add_u64 v[136:137], v[136:137], 0, s[2:3]
	v_lshl_add_u64 v[136:137], v[136:137], 0, v[176:177]
	v_ashrrev_i32_e32 v147, 31, v146
	v_readlane_b32 s10, v254, 43
	v_lshlrev_b64 v[178:179], 11, v[146:147]
	v_readlane_b32 s11, v254, 44
	s_and_b64 vcc, exec, s[8:9]
	s_nop 0
	v_lshl_add_u64 v[138:139], s[10:11], 0, v[178:179]
	v_lshl_add_u64 v[144:145], v[138:139], 0, v[176:177]
	s_cbranch_vccnz .LBB0_680

.LBB0_682:
	v_lshlrev_b64 v[180:181], 12, v[146:147]
	v_mov_b64_e32 v[140:141], v[226:227]
	v_mov_b64_e32 v[142:143], v[228:229]
	v_mov_b64_e32 v[136:137], v[230:231]
	v_mov_b64_e32 v[138:139], v[232:233]
	v_mov_b64_e32 v[132:133], v[234:235]
	v_mov_b64_e32 v[134:135], v[236:237]
	v_mov_b64_e32 v[128:129], v[238:239]
	v_mov_b64_e32 v[130:131], v[240:241]
	v_lshlrev_b32_e32 v146, 16, v140
	v_and_b32_e32 v147, 0xffff0000, v140
	v_lshlrev_b32_e32 v140, 16, v141
	v_and_b32_e32 v141, 0xffff0000, v141
	v_lshlrev_b32_e32 v148, 16, v142
	v_and_b32_e32 v149, 0xffff0000, v142
	v_lshlrev_b32_e32 v150, 16, v143
	v_and_b32_e32 v151, 0xffff0000, v143
	v_pk_mul_f32 v[140:141], v[46:47], v[140:141]
	v_pk_mul_f32 v[142:143], v[44:45], v[146:147]
	v_pk_mul_f32 v[146:147], v[42:43], v[150:151]
	v_pk_mul_f32 v[148:149], v[40:41], v[148:149]
	s_cmp_lt_i32 s93, 7
	s_mov_b64 s[10:11], -1
	s_cbranch_scc1 .LBB0_688
	s_cmp_lg_u32 s93, 7
	s_cbranch_scc0 .LBB0_685
	v_lshlrev_b32_e32 v150, 16, v132
	v_and_b32_e32 v151, 0xffff0000, v132
	v_pk_add_f32 v[150:151], v[142:143], v[150:151]
	v_lshlrev_b32_e32 v192, 16, v135
	v_and_b32_e32 v193, 0xffff0000, v135
	v_pk_add_f32 v[196:197], v[146:147], v[192:193]
	v_cvt_pk_bf16_f32 v192, v150, v151
	v_lshl_add_u64 v[150:151], s[18:19], 0, v[180:181]
	v_lshlrev_b32_e32 v154, 16, v133
	v_and_b32_e32 v155, 0xffff0000, v133
	v_lshlrev_b32_e32 v182, 16, v134
	v_and_b32_e32 v183, 0xffff0000, v134
	v_lshl_add_u64 v[150:151], v[174:175], 1, v[150:151]
	v_pk_add_f32 v[154:155], v[140:141], v[154:155]
	v_pk_add_f32 v[182:183], v[148:149], v[182:183]
	v_add_co_u32_e32 v150, vcc, 0xbf00000, v150
	v_cvt_pk_bf16_f32 v193, v154, v155
	v_cvt_pk_bf16_f32 v194, v182, v183
	v_cvt_pk_bf16_f32 v195, v196, v197
	v_addc_co_u32_e32 v151, vcc, 0, v151, vcc
	flat_store_dwordx4 v[150:151], v[192:195] offset:2048
	s_mov_b64 s[10:11], 0

.LBB0_699:
	v_lshlrev_b64 v[180:181], 12, v[146:147]
	s_mov_b32 s98, 0x108000
	s_mov_b32 s99, 0
	v_lshl_add_u64 v[218:219], v[214:215], 0, s[98:99]
	global_load_dwordx4 v[226:229], v[218:219], off
	global_load_dwordx4 v[230:233], v[218:219], off offset:256
	s_cmp_lg_u32 s93, 8
	s_cbranch_scc1 .Lbrp_skip_6
	s_mov_b32 s98, 0x58000
	v_lshl_add_u64 v[218:219], v[216:217], 0, s[98:99]
	global_load_dwordx4 v[234:237], v[218:219], off
	global_load_dwordx4 v[238:241], v[218:219], off offset:256
.Lbrp_skip_6:
	s_waitcnt vmcnt(0) lgkmcnt(0)
	v_lshlrev_b32_e32 v146, 16, v140
	v_and_b32_e32 v147, 0xffff0000, v140
	v_lshlrev_b32_e32 v140, 16, v141
	v_and_b32_e32 v141, 0xffff0000, v141
	v_lshlrev_b32_e32 v148, 16, v142
	v_and_b32_e32 v149, 0xffff0000, v142
	v_lshlrev_b32_e32 v150, 16, v143
	v_and_b32_e32 v151, 0xffff0000, v143
	v_pk_mul_f32 v[140:141], v[30:31], v[140:141]
	v_pk_mul_f32 v[142:143], v[28:29], v[146:147]
	v_pk_mul_f32 v[146:147], v[26:27], v[150:151]
	v_pk_mul_f32 v[148:149], v[24:25], v[148:149]
	s_cmp_lt_i32 s93, 7
	s_mov_b64 s[10:11], -1
	s_cbranch_scc1 .LBB0_705
	s_cmp_lg_u32 s93, 7
	s_cbranch_scc0 .LBB0_702
	v_lshlrev_b32_e32 v150, 16, v132
	v_and_b32_e32 v151, 0xffff0000, v132
	v_pk_add_f32 v[150:151], v[142:143], v[150:151]
	v_lshlrev_b32_e32 v192, 16, v135
	v_and_b32_e32 v193, 0xffff0000, v135
	v_pk_add_f32 v[196:197], v[146:147], v[192:193]
	v_cvt_pk_bf16_f32 v192, v150, v151
	v_lshl_add_u64 v[150:151], s[18:19], 0, v[180:181]
	v_lshlrev_b32_e32 v154, 16, v133
	v_and_b32_e32 v155, 0xffff0000, v133
	v_lshlrev_b32_e32 v182, 16, v134
	v_and_b32_e32 v183, 0xffff0000, v134
	v_lshl_add_u64 v[150:151], v[174:175], 1, v[150:151]
	v_pk_add_f32 v[154:155], v[140:141], v[154:155]
	v_pk_add_f32 v[182:183], v[148:149], v[182:183]
	v_add_co_u32_e32 v150, vcc, 0xbf00000, v150
	v_cvt_pk_bf16_f32 v193, v154, v155
	v_cvt_pk_bf16_f32 v194, v182, v183
	v_cvt_pk_bf16_f32 v195, v196, v197
	v_addc_co_u32_e32 v151, vcc, 0, v151, vcc
	flat_store_dwordx4 v[150:151], v[192:195] offset:2048
	s_mov_b64 s[10:11], 0

.LBB0_712:
	v_lshl_add_u64 v[140:141], s[18:19], 0, v[180:181]
	v_lshl_add_u64 v[140:141], v[140:141], 0, v[182:183]
	v_cvt_pk_bf16_f32 v136, v144, v145
	v_cvt_pk_bf16_f32 v137, v146, v147
	v_cvt_pk_bf16_f32 v138, v148, v149
	v_cvt_pk_bf16_f32 v139, v150, v151
	v_lshl_add_u64 v[140:141], v[140:141], 0, v[176:177]
	flat_store_dwordx4 v[140:141], v[136:139] offset:256
	v_add_u32_e32 v146, 0xb0, v172
	s_movk_i32 s10, 0x1800
	v_mov_b64_e32 v[136:137], s[44:45]
	v_mad_i64_i32 v[136:137], s[10:11], v146, s10, v[136:137]
	v_lshl_add_u64 v[136:137], v[136:137], 0, s[2:3]
	v_lshl_add_u64 v[136:137], v[136:137], 0, v[176:177]
	v_ashrrev_i32_e32 v147, 31, v146
	v_readlane_b32 s10, v254, 43
	v_lshlrev_b64 v[148:149], 11, v[146:147]
	v_readlane_b32 s11, v254, 44
	s_and_b64 vcc, exec, s[8:9]
	s_nop 0
	v_lshl_add_u64 v[138:139], s[10:11], 0, v[148:149]
	v_lshl_add_u64 v[144:145], v[138:139], 0, v[176:177]
	s_cbranch_vccnz .LBB0_714

.LBB0_716:
	v_lshlrev_b64 v[150:151], 12, v[146:147]
	v_mov_b64_e32 v[140:141], v[226:227]
	v_mov_b64_e32 v[142:143], v[228:229]
	v_mov_b64_e32 v[136:137], v[230:231]
	v_mov_b64_e32 v[138:139], v[232:233]
	v_mov_b64_e32 v[132:133], v[234:235]
	v_mov_b64_e32 v[134:135], v[236:237]
	v_mov_b64_e32 v[128:129], v[238:239]
	v_mov_b64_e32 v[130:131], v[240:241]
	v_lshlrev_b32_e32 v146, 16, v140
	v_and_b32_e32 v147, 0xffff0000, v140
	v_lshlrev_b32_e32 v140, 16, v141
	v_and_b32_e32 v141, 0xffff0000, v141
	v_lshlrev_b32_e32 v154, 16, v142
	v_and_b32_e32 v155, 0xffff0000, v142
	v_lshlrev_b32_e32 v176, 16, v143
	v_and_b32_e32 v177, 0xffff0000, v143
	v_pk_mul_f32 v[140:141], v[14:15], v[140:141]
	v_pk_mul_f32 v[142:143], v[12:13], v[146:147]
	v_pk_mul_f32 v[146:147], v[10:11], v[176:177]
	v_pk_mul_f32 v[176:177], v[8:9], v[154:155]
	s_cmp_lt_i32 s93, 7
	s_mov_b64 s[8:9], -1
	s_cbranch_scc1 .LBB0_722
	s_cmp_lg_u32 s93, 7
	s_cbranch_scc0 .LBB0_719
	v_lshlrev_b32_e32 v154, 16, v132
	v_and_b32_e32 v155, 0xffff0000, v132
	v_lshlrev_b32_e32 v132, 16, v133
	v_and_b32_e32 v133, 0xffff0000, v133
	v_pk_add_f32 v[178:179], v[140:141], v[132:133]
	v_pk_add_f32 v[132:133], v[142:143], v[154:155]
	v_lshlrev_b32_e32 v154, 16, v134
	v_and_b32_e32 v155, 0xffff0000, v134
	v_lshlrev_b32_e32 v134, 16, v135
	v_and_b32_e32 v135, 0xffff0000, v135
	v_pk_add_f32 v[180:181], v[146:147], v[134:135]
	v_pk_add_f32 v[134:135], v[176:177], v[154:155]
	v_lshl_add_u64 v[154:155], s[18:19], 0, v[150:151]
	v_lshl_add_u64 v[154:155], v[174:175], 1, v[154:155]
	v_add_co_u32_e32 v154, vcc, 0xbf00000, v154
	v_cvt_pk_bf16_f32 v132, v132, v133
	v_cvt_pk_bf16_f32 v133, v178, v179
	v_cvt_pk_bf16_f32 v134, v134, v135
	v_cvt_pk_bf16_f32 v135, v180, v181
	v_addc_co_u32_e32 v155, vcc, 0, v155, vcc
	flat_store_dwordx4 v[154:155], v[132:135] offset:2048
	s_mov_b64 s[8:9], 0
